# MLA tile loop LDS-DMA issue in SGPR-base + 32-bit lane offset form (removes 5 v_lshl_add_u64 per softmax block)
# speedup vs baseline: 1.0201x; 1.0201x over previous
.LBB0_668:
	s_and_b64 vcc, exec, s[2:3]
	s_barrier
	s_setprio 0
	s_cbranch_vccnz .LBB0_670
	s_mov_b32 m0, s89
	s_add_i32 s8, s89, s95
	global_load_lds_dwordx4 v134, s[52:53]
	s_mov_b32 m0, s91
	s_nop 0
	global_load_lds_dwordx4 v154, s[52:53]
	s_mov_b32 m0, s92
	s_add_u32 s52, s52, 0x40000
	s_addc_u32 s53, s53, 0
	global_load_lds_dwordx4 v144, s[54:55]
	s_add_i32 m0, s8, 0xc000
	s_add_u32 s54, s54, 0x100000
	s_addc_u32 s55, s55, 0
	global_load_lds_dwordx4 v142, s[48:49]
	s_add_i32 m0, s8, 0xc400
	s_nop 0
	global_load_lds_dwordx4 v152, s[48:49]
	s_add_u32 s48, s48, 0x40000
	s_addc_u32 s49, s49, 0
.LBB0_670:
	s_and_b64 vcc, exec, s[6:7]
	s_cbranch_vccnz .LBB0_672
	s_add_i32 m0, s89, 0x4000
	s_add_i32 s8, s89, s94
	global_load_lds_dwordx4 v134, s[52:53]
	s_add_i32 m0, s89, 0x4400
	s_nop 0
	global_load_lds_dwordx4 v154, s[52:53]
	s_add_i32 m0, s90, 0xa000
	s_add_u32 s52, s52, 0x40000
	s_addc_u32 s53, s53, 0
	global_load_lds_dwordx4 v144, s[54:55]
	s_add_i32 m0, s8, 0xc000
	s_add_u32 s54, s54, 0x100000
	s_addc_u32 s55, s55, 0
	global_load_lds_dwordx4 v142, s[48:49]
	s_add_i32 m0, s8, 0xc400
	s_nop 0
	global_load_lds_dwordx4 v152, s[48:49]
	s_add_u32 s48, s48, 0x40000
	s_addc_u32 s49, s49, 0

.LBB0_680:
	s_and_b64 vcc, exec, s[2:3]
	s_barrier
	s_setprio 0
	s_cbranch_vccnz .LBB0_682
	s_add_i32 m0, s89, 0x4000
	s_add_i32 s8, s89, s94
	global_load_lds_dwordx4 v134, s[52:53]
	s_add_i32 m0, s89, 0x4400
	s_nop 0
	global_load_lds_dwordx4 v154, s[52:53]
	s_add_i32 m0, s90, 0xa000
	s_add_u32 s52, s52, 0x40000
	s_addc_u32 s53, s53, 0
	global_load_lds_dwordx4 v144, s[54:55]
	s_add_i32 m0, s8, 0xc000
	s_add_u32 s54, s54, 0x100000
	s_addc_u32 s55, s55, 0
	global_load_lds_dwordx4 v142, s[48:49]
	s_add_i32 m0, s8, 0xc400
	s_nop 0
	global_load_lds_dwordx4 v152, s[48:49]
	s_add_u32 s48, s48, 0x40000
	s_addc_u32 s49, s49, 0
.LBB0_682:
	s_cmpk_gt_u32 s93, 0x80
	s_cselect_b64 s[56:57], -1, 0
	s_cmpk_lt_u32 s93, 0x81
	s_cselect_b64 s[8:9], -1, 0
	s_and_b64 s[8:9], s[44:45], s[8:9]
	s_andn2_b64 vcc, exec, s[8:9]
	s_cbranch_vccnz .LBB0_684
	s_mov_b32 m0, s89
	s_add_i32 s8, s89, s12
	global_load_lds_dwordx4 v134, s[52:53]
	s_mov_b32 m0, s91
	s_nop 0
	global_load_lds_dwordx4 v154, s[52:53]
	s_mov_b32 m0, s92
	s_add_u32 s52, s52, 0x40000
	s_addc_u32 s53, s53, 0
	global_load_lds_dwordx4 v144, s[54:55]
	s_add_i32 m0, s8, 0xc000
	s_add_u32 s54, s54, 0x100000
	s_addc_u32 s55, s55, 0
	global_load_lds_dwordx4 v142, s[48:49]
	s_add_i32 m0, s8, 0xc400
	s_nop 0
	global_load_lds_dwordx4 v152, s[48:49]
	s_add_u32 s48, s48, 0x40000
	s_addc_u32 s49, s49, 0
